# route_a prologue: last three key-row staging loads issued with the first five (three serialized round trips removed)
# speedup vs baseline: 1.0148x; 1.0000x over previous
.LBB0_942:
	s_or_b64 exec, exec, s[0:1]
	v_readlane_b32 s4, v248, 40
	v_readlane_b32 s0, v247, 0
	v_readlane_b32 s5, v248, 41
	v_readlane_b32 s6, v248, 42
	v_readlane_b32 s7, v248, 43
	v_readlane_b32 s8, v248, 44
	v_readlane_b32 s9, v248, 45
	s_and_b32 s2, s0, 1
	v_readlane_b32 s10, v248, 46
	v_readlane_b32 s11, v248, 47
	s_mov_b64 s[4:5], s[8:9]
	v_readlane_b32 s1, v247, 1
	s_cmp_eq_u32 s2, 0
	s_mov_b64 s[6:7], s[10:11]
	s_waitcnt vmcnt(5)
	v_add_u32_e32 v4, 0x100, v130
	s_cselect_b32 s1, s5, s7
	s_cselect_b32 s0, s4, s6
	v_mov_b32_e32 v85, 0
	v_lshrrev_b32_e32 v26, 4, v4
	s_waitcnt lgkmcnt(0)
	v_lshl_add_u64 v[0:1], s[0:1], 0, v[84:85]
	v_lshlrev_b32_e32 v2, 1, v159
	v_mov_b32_e32 v3, v85
	v_lshlrev_b32_e32 v4, 8, v26
	v_mov_b32_e32 v5, v85
	v_lshl_add_u64 v[2:3], v[0:1], 0, v[2:3]
	v_lshl_add_u64 v[4:5], v[0:1], 0, v[4:5]
	s_barrier
	s_barrier
	global_load_dwordx4 v[6:9], v[2:3], off
	global_load_dwordx4 v[10:13], v[4:5], off
	v_add_u32_e32 v2, 0x200, v130
	v_add_u32_e32 v4, 0x300, v130
	v_lshrrev_b32_e32 v27, 4, v2
	v_lshrrev_b32_e32 v28, 4, v4
	v_lshlrev_b32_e32 v2, 8, v27
	v_mov_b32_e32 v3, v85
	v_lshlrev_b32_e32 v4, 8, v28
	v_mov_b32_e32 v5, v85
	v_lshl_add_u64 v[2:3], v[0:1], 0, v[2:3]
	v_lshl_add_u64 v[4:5], v[0:1], 0, v[4:5]
	global_load_dwordx4 v[14:17], v[2:3], off
	global_load_dwordx4 v[18:21], v[4:5], off
	v_or_b32_e32 v5, 0x400, v130
	v_lshrrev_b32_e32 v29, 4, v5
	v_lshlrev_b32_e32 v2, 8, v29
	v_mov_b32_e32 v3, v85
	v_lshl_add_u64 v[2:3], v[0:1], 0, v[2:3]
	global_load_dwordx4 v[22:25], v[2:3], off
	v_add_u32_e32 v42, 0x500, v130
	v_lshrrev_b32_e32 v48, 4, v42
	v_lshlrev_b32_e32 v42, 8, v48
	v_mov_b32_e32 v43, v85
	v_lshl_add_u64 v[42:43], v[0:1], 0, v[42:43]
	global_load_dwordx4 v[30:33], v[42:43], off
	v_mov_b32_e32 v44, 0x6000
	v_lshl_or_b32 v44, v136, 8, v44
	v_mov_b32_e32 v45, v85
	v_lshl_add_u64 v[44:45], v[0:1], 0, v[44:45]
	global_load_dwordx4 v[34:37], v[44:45], off
	v_add_u32_e32 v46, 0x700, v130
	v_lshrrev_b32_e32 v49, 4, v46
	v_lshlrev_b32_e32 v46, 8, v49
	v_mov_b32_e32 v47, v85
	v_lshl_add_u64 v[46:47], v[0:1], 0, v[46:47]
	global_load_dwordx4 v[38:41], v[46:47], off
	s_movk_i32 s4, 0x110
	s_movk_i32 s0, 0x700
	s_movk_i32 s3, 0x200
	v_mad_u32_u24 v4, v136, s4, v84
	v_cmp_gt_u32_e32 vcc, s0, v5
	v_readlane_b32 s12, v248, 48
	v_readlane_b32 s13, v248, 49
	v_readlane_b32 s14, v248, 50
	v_readlane_b32 s15, v248, 51
	v_readlane_b32 s16, v248, 52
	v_readlane_b32 s17, v248, 53
	v_readlane_b32 s18, v248, 54
	v_readlane_b32 s19, v248, 55
	v_mad_u32_u24 v2, v26, s4, v84
	v_mad_u32_u24 v3, v27, s4, v84
	v_mad_u32_u24 v26, v28, s4, v84
	v_mad_u32_u24 v27, v29, s4, v84
	s_waitcnt vmcnt(7)
	ds_write_b128 v4, v[6:9]
	s_waitcnt vmcnt(6)
	ds_write_b128 v2, v[10:13]
	s_waitcnt vmcnt(5)
	ds_write_b128 v3, v[14:17]
	s_waitcnt vmcnt(4)
	ds_write_b128 v26, v[18:21]
	s_waitcnt vmcnt(3)
	ds_write_b128 v27, v[22:25]
	s_and_saveexec_b64 s[0:1], vcc
	s_cbranch_execz .LBB0_946
	v_mad_u32_u24 v48, v48, s4, v84
	v_mad_u32_u24 v49, v49, s4, v84
	s_waitcnt vmcnt(2)
	ds_write_b128 v48, v[30:33]
	s_waitcnt vmcnt(1)
	ds_write_b128 v4, v[34:37] offset:26112
	s_waitcnt vmcnt(0)
	ds_write_b128 v49, v[38:41]
